# GEMM phase prologue: second staging batch issued together with the first (first wait vmcnt 2->8)
# baseline (speedup 1.0000x reference)
; #define PG8_STAGE(bufoff, gbase, voff) do { _Pragma("unroll") for (int _i = 0; _i < 2; ++_i) \
;         __builtin_amdgcn_global_load_lds((const unsigned*)((const char*)(gbase) + (voff)[_i]), (PG8_LAS unsigned*)(lds + (bufoff) + ldsw + _i * 8192), 16, 0, 0); } while (0)
; #define PG8_WAIT_V(n) asm volatile("s_waitcnt vmcnt(" #n ")" ::: "memory")
; #define PG8_BAR __builtin_amdgcn_s_barrier()
; template <class Epi, class Sched, bool ALIGN_EPI = false, bool SP2 = false>
; __device__ __forceinline__ void gemm_phase(PG8_LAS unsigned char* lds, const Gemm g, const Sched& S, const Epi& E) {
;     ...
;     for (int i = 0; i < 2; ++i) { int R, C; stage_rc(tid * 16 + i * 8192, R, C); const int Rb = Epi::PERM ? ((R & ~31) + perm32(R & 31)) : R;
;         voffA[i] = (unsigned)(R * K + C) * 2u; voffB[i] = (unsigned)(Rb * K + C) * 2u; }
;     const size_t kstep = (size_t)(BK * 2);
;     const size_t hstep = (size_t)HALF * K * 2;
;     const size_t tstep = 2 * hstep;
;     const unsigned ldsw = (unsigned)wid * 1024u;
;     const int aoff = lds_byte(wr * 64 + fr, fq * 8), boff = lds_byte(wc * 32 + fr, fq * 8);
;     ...
;         PG8_STAGE(PG8_SB(1, 0), cB + kstep, voffB); PG8_STAGE(PG8_SA(1, 0), cA + kstep, voffA); PG8_STAGE(PG8_SB(1, 1), cB + hstep + kstep, voffB);
;         PG8_WAIT_V(6); PG8_BAR;
.LBB0_159:
	v_bfe_u32 v22, v20, 4, 2
	v_and_b32_e32 v21, 15, v20
	v_lshlrev_b32_e32 v0, 4, v22
	v_lshlrev_b32_e32 v20, 2, v20
	s_lshl_b32 s7, s7, 5
	v_lshl_or_b32 v177, s10, 6, v21
	v_lshl_or_b32 v21, v21, 6, v0
	s_lshl_b32 s10, s10, 13
	v_and_b32_e32 v20, 32, v20
	s_and_b32 s7, s7, 0x60
	s_add_i32 m0, s45, 0x18000
	v_lshl_add_u64 v[12:13], v[12:13], 0, s[20:21]
	v_bitop3_b32 v23, v21, s10, v20 bitop3:0xde
	s_lshl_b32 s10, s7, 7
	global_load_lds_dwordx4 v[12:13], off
	v_lshl_add_u64 v[10:11], v[10:11], 0, s[20:21]
	s_add_i32 m0, s45, 0x1a000
	s_add_i32 s49, s45, 0x8000
	s_add_i32 s50, s45, 0xa000
	v_bitop3_b32 v194, v21, s10, v20 bitop3:0xde
	global_load_lds_dwordx4 v[10:11], off
	v_lshl_add_u64 v[2:3], v[2:3], 0, s[20:21]
	s_mov_b32 m0, s49
	s_add_u32 s10, s42, 0x40080
	global_load_lds_dwordx4 v[2:3], off
	v_lshl_add_u64 v[2:3], v[8:9], 0, s[20:21]
	s_mov_b32 m0, s50
	s_addc_u32 s11, s43, 0
	global_load_lds_dwordx4 v[2:3], off
	s_add_i32 m0, s45, 0x1c000
	v_lshl_add_u64 v[2:3], s[10:11], 0, v[162:163]
	global_load_lds_dwordx4 v[2:3], off
	v_lshl_add_u64 v[2:3], s[10:11], 0, v[158:159]
	s_add_i32 m0, s45, 0x1e000
	v_readlane_b32 s12, v252, 28
	global_load_lds_dwordx4 v[2:3], off
	v_readlane_b32 s13, v252, 29
	v_and_b32_e32 v2, 1, v18
	s_waitcnt vmcnt(8)
	s_barrier
	s_waitcnt vmcnt(6)
	s_cmpk_lt_u32 s6, 0x100
	v_lshl_add_u64 v[180:181], s[12:13], 0, v[0:1]
	v_lshlrev_b32_e32 v0, 14, v18
	v_and_b32_e32 v0, 0xffff8000, v0
	v_lshl_add_u32 v0, v17, 11, v0
	v_lshl_or_b32 v0, v2, 6, v0
	v_lshl_add_u32 v182, v19, 1, v0
	v_lshlrev_b32_e32 v0, 14, v14
	v_and_b32_e32 v0, 0xffff8000, v0
	v_lshl_add_u32 v0, v15, 11, v0
	v_and_b32_e32 v2, 1, v14
	v_lshl_or_b32 v195, v22, 3, s7
	v_lshl_or_b32 v0, v2, 6, v0
	v_readlane_b32 s6, v254, 41
	s_cselect_b64 s[10:11], -1, 0
	v_mov_b32_e32 v183, v1
	v_lshl_add_u32 v184, v16, 1, v0
	v_mov_b32_e32 v185, v1
	s_mov_b32 s51, 0
	v_add_u32_e32 v196, 0, v23
	v_readlane_b32 s52, v254, 28
	s_mov_b32 s36, s6
	s_barrier
	v_readlane_b32 s7, v254, 42
	s_branch .LBB0_162

; #define PG8_STAGE(bufoff, gbase, voff) do { _Pragma("unroll") for (int _i = 0; _i < 2; ++_i) \
;         __builtin_amdgcn_global_load_lds((const unsigned*)((const char*)(gbase) + (voff)[_i]), (PG8_LAS unsigned*)(lds + (bufoff) + ldsw + _i * 8192), 16, 0, 0); } while (0)
; #define PG8_WAIT_V(n) asm volatile("s_waitcnt vmcnt(" #n ")" ::: "memory")
; #define PG8_BAR __builtin_amdgcn_s_barrier()
; template <class Epi, class Sched, bool ALIGN_EPI = false, bool SP2 = false>
; __device__ __forceinline__ void gemm_phase(PG8_LAS unsigned char* lds, const Gemm g, const Sched& S, const Epi& E) {
;     ...
;     for (int i = 0; i < 2; ++i) { int R, C; stage_rc(tid * 16 + i * 8192, R, C); const int Rb = Epi::PERM ? ((R & ~31) + perm32(R & 31)) : R;
;         voffA[i] = (unsigned)(R * K + C) * 2u; voffB[i] = (unsigned)(Rb * K + C) * 2u; }
;     const size_t kstep = (size_t)(BK * 2);
;     const size_t hstep = (size_t)HALF * K * 2;
;     const size_t tstep = 2 * hstep;
;     const unsigned ldsw = (unsigned)wid * 1024u;
;     const int aoff = lds_byte(wr * 64 + fr, fq * 8), boff = lds_byte(wc * 32 + fr, fq * 8);
;     ...
;         PG8_STAGE(PG8_SB(1, 0), cB + kstep, voffB); PG8_STAGE(PG8_SA(1, 0), cA + kstep, voffA); PG8_STAGE(PG8_SB(1, 1), cB + hstep + kstep, voffB);
;         PG8_WAIT_V(6); PG8_BAR;
.LBB0_189:
	s_add_i32 m0, s52, 0x18000
	v_lshl_add_u64 v[8:9], v[8:9], 0, s[20:21]
	global_load_lds_dwordx4 v[8:9], off
	v_lshl_add_u64 v[8:9], v[10:11], 0, s[20:21]
	s_add_i32 m0, s52, 0x1a000
	s_add_i32 s56, s52, 0x8000
	global_load_lds_dwordx4 v[8:9], off
	v_lshl_add_u64 v[8:9], v[16:17], 0, s[20:21]
	s_mov_b32 m0, s56
	s_add_i32 s57, s52, 0xa000
	global_load_lds_dwordx4 v[8:9], off
	v_lshl_add_u64 v[8:9], v[18:19], 0, s[20:21]
	s_mov_b32 m0, s57
	v_cndmask_b32_e64 v136, 0.5, 1.0, s[2:3]
	global_load_lds_dwordx4 v[8:9], off
	s_add_i32 m0, s52, 0x1c000
	v_lshl_add_u64 v[8:9], v[12:13], 0, s[20:21]
	global_load_lds_dwordx4 v[8:9], off
	v_lshl_add_u64 v[8:9], v[14:15], 0, s[20:21]
	s_add_i32 m0, s52, 0x1e000
	s_and_b32 s58, s8, 3
	global_load_lds_dwordx4 v[8:9], off
	v_bfe_u32 v8, v20, 4, 2
	v_and_b32_e32 v9, 15, v20
	v_lshlrev_b32_e32 v10, 4, v8
	v_lshl_or_b32 v177, s7, 6, v9
	v_lshl_or_b32 v9, v9, 6, v10
	v_lshlrev_b32_e32 v10, 2, v20
	s_lshl_b32 s2, s7, 13
	v_and_b32_e32 v10, 32, v10
	v_bitop3_b32 v11, v9, s2, v10 bitop3:0xde
	s_lshl_b32 s2, s58, 12
	s_lshr_b32 s59, s9, 6
	v_bitop3_b32 v200, v9, s2, v10 bitop3:0xde
	v_lshlrev_b32_e32 v9, 2, v8
	v_cmp_eq_u32_e64 s[42:43], 0, v8
	v_add_u32_e32 v8, v24, v25
	s_add_i32 s60, s59, -2
	v_lshl_or_b32 v201, s58, 5, v9
	v_add_lshl_u32 v8, v8, v26, 1
	v_mov_b32_e32 v9, v1
	s_waitcnt vmcnt(8)
	s_barrier
	s_waitcnt vmcnt(6)
	s_cmpk_lt_u32 s6, 0x100
	v_lshl_add_u64 v[140:141], s[12:13], 0, v[8:9]
	v_add_u32_e32 v8, v21, v22
	s_cselect_b64 s[46:47], -1, 0
	s_waitcnt lgkmcnt(0)
	s_cmp_lg_u64 s[10:11], 0
	v_add_lshl_u32 v8, v8, v23, 1
	s_mov_b32 s61, 0
	s_cselect_b64 s[48:49], -1, 0
	v_mov_b32_e32 v138, v136
	v_mov_b32_e32 v139, v136
	v_lshl_add_u64 v[142:143], s[12:13], 0, v[8:9]
	v_add_u32_e32 v210, 0, v11
	v_readlane_b32 s14, v254, 31
	v_readlane_b32 s15, v254, 24
	s_barrier
	s_branch .LBB0_192

; #define PG8_STAGE(bufoff, gbase, voff) do { _Pragma("unroll") for (int _i = 0; _i < 2; ++_i) \
;         __builtin_amdgcn_global_load_lds((const unsigned*)((const char*)(gbase) + (voff)[_i]), (PG8_LAS unsigned*)(lds + (bufoff) + ldsw + _i * 8192), 16, 0, 0); } while (0)
; #define PG8_WAIT_V(n) asm volatile("s_waitcnt vmcnt(" #n ")" ::: "memory")
; #define PG8_BAR __builtin_amdgcn_s_barrier()
; template <class Epi, class Sched, bool ALIGN_EPI = false, bool SP2 = false>
; __device__ __forceinline__ void gemm_phase(PG8_LAS unsigned char* lds, const Gemm g, const Sched& S, const Epi& E) {
;     ...
;     for (int i = 0; i < 2; ++i) { int R, C; stage_rc(tid * 16 + i * 8192, R, C); const int Rb = Epi::PERM ? ((R & ~31) + perm32(R & 31)) : R;
;         voffA[i] = (unsigned)(R * K + C) * 2u; voffB[i] = (unsigned)(Rb * K + C) * 2u; }
;     const size_t kstep = (size_t)(BK * 2);
;     const size_t hstep = (size_t)HALF * K * 2;
;     const size_t tstep = 2 * hstep;
;     const unsigned ldsw = (unsigned)wid * 1024u;
;     const int aoff = lds_byte(wr * 64 + fr, fq * 8), boff = lds_byte(wc * 32 + fr, fq * 8);
;     ...
;         PG8_STAGE(PG8_SB(1, 0), cB + kstep, voffB); PG8_STAGE(PG8_SA(1, 0), cA + kstep, voffA); PG8_STAGE(PG8_SB(1, 1), cB + hstep + kstep, voffB);
;         PG8_WAIT_V(6); PG8_BAR;
.LBB0_251:
	s_lshl_b32 s10, s10, 5
	s_and_b32 s13, s10, 0x60
	s_add_i32 m0, s44, 0x18000
	v_lshl_add_u64 v[12:13], v[12:13], 0, s[20:21]
	s_lshl_b32 s12, s7, 13
	s_lshl_b32 s14, s13, 7
	global_load_lds_dwordx4 v[12:13], off
	v_lshl_add_u64 v[10:11], v[10:11], 0, s[20:21]
	s_add_i32 m0, s44, 0x1a000
	s_add_i32 s48, s44, 0x8000
	s_add_i32 s49, s44, 0xa000
	global_load_lds_dwordx4 v[10:11], off
	v_lshl_add_u64 v[2:3], v[2:3], 0, s[20:21]
	s_mov_b32 m0, s48
	s_add_u32 s10, s40, 0x40080
	global_load_lds_dwordx4 v[2:3], off
	v_lshl_add_u64 v[2:3], v[8:9], 0, s[20:21]
	s_mov_b32 m0, s49
	s_addc_u32 s11, s41, 0
	global_load_lds_dwordx4 v[2:3], off
	s_add_i32 m0, s44, 0x1c000
	v_lshl_add_u64 v[2:3], s[10:11], 0, v[182:183]
	global_load_lds_dwordx4 v[2:3], off
	v_lshl_add_u64 v[2:3], s[10:11], 0, v[178:179]
	s_add_i32 m0, s44, 0x1e000
	s_cmpk_lt_u32 s6, 0x100
	global_load_lds_dwordx4 v[2:3], off
	v_and_b32_e32 v2, 15, v14
	v_bfe_u32 v3, v14, 4, 2
	v_lshl_or_b32 v177, s7, 6, v2
	v_readlane_b32 s6, v252, 28
	v_lshlrev_b32_e32 v0, 4, v3
	v_readlane_b32 s7, v252, 29
	v_lshl_or_b32 v2, v2, 6, v0
	v_lshlrev_b32_e32 v8, 2, v14
	v_lshl_add_u64 v[186:187], s[6:7], 0, v[0:1]
	v_lshlrev_b32_e32 v0, 14, v19
	v_and_b32_e32 v8, 32, v8
	v_and_b32_e32 v0, 0xffff8000, v0
	v_bitop3_b32 v9, v2, s12, v8 bitop3:0xde
	v_bitop3_b32 v210, v2, s14, v8 bitop3:0xde
	v_lshl_add_u32 v0, v18, 11, v0
	v_and_b32_e32 v2, 1, v19
	v_lshl_or_b32 v0, v2, 6, v0
	v_lshl_add_u32 v188, v20, 1, v0
	v_lshlrev_b32_e32 v0, 14, v15
	v_and_b32_e32 v0, 0xffff8000, v0
	s_waitcnt vmcnt(8)
	s_barrier
	s_waitcnt vmcnt(6)
	v_lshl_add_u32 v0, v16, 11, v0
	v_and_b32_e32 v2, 1, v15
	v_lshl_or_b32 v0, v2, 6, v0
	v_readlane_b32 s6, v254, 37
	s_cselect_b64 s[10:11], -1, 0
	v_lshl_or_b32 v211, v3, 3, s13
	v_mov_b32_e32 v189, v1
	v_lshl_add_u32 v190, v17, 1, v0
	v_mov_b32_e32 v191, v1
	s_mov_b32 s50, 0
	v_add_u32_e32 v212, 0, v9
	v_readlane_b32 s51, v254, 25
	s_mov_b32 s52, s6
	s_barrier
	v_readlane_b32 s7, v254, 38
	s_branch .LBB0_254
